# gdn_prep: beta/decay-gate evaluation moved out of the conv loop (12 of 64 lanes, dependent loads) into one dense pass after it (48 of 64 lanes, two tokens per lane); same arithmetic
# speedup vs baseline: 1.0113x; 1.0113x over previous
.LBB0_187:
	s_or_b64 exec, exec, s[6:7]
	s_add_u32 s76, s28, 0xac00000
	s_addc_u32 s77, s29, 0
	s_lshl_b32 s6, s2, 3
	v_add_u32_e32 v178, s6, v220
	s_movk_i32 s34, 0x3000
	v_writelane_b32 v255, s6, 45
	v_cmp_gt_i32_e32 vcc, s34, v178
	v_lshlrev_b32_e32 v174, 2, v211
	s_waitcnt lgkmcnt(0)
	s_barrier
	s_and_saveexec_b64 s[10:11], vcc
	s_cbranch_execz .LBB0_240
	v_lshrrev_b32_e32 v34, 4, v210
	v_mov_b32_e32 v38, 0
	v_or_b32_e32 v36, v174, v34
	v_and_b32_e32 v4, 48, v210
	v_mov_b32_e32 v5, v38
	v_add_u32_e32 v2, -4, v36
	v_mov_b32_e32 v3, v38
	v_lshl_add_u64 v[4:5], s[28:29], 0, v[4:5]
	v_mov_b32_e32 v175, v38
	v_lshlrev_b32_e32 v6, 3, v210
	v_cmp_lt_u32_e32 vcc, 2, v211
	v_lshl_add_u64 v[4:5], v[4:5], 0, v[174:175]
	s_mov_b64 s[8:9], 0xfd00000
	v_lshlrev_b64 v[2:3], 2, v[2:3]
	v_cmp_ne_u32_e64 s[6:7], 0, v211
	v_lshl_add_u64 v[40:41], v[4:5], 0, s[8:9]
	s_lshl_b32 s35, s30, 3
	v_lshl_add_u64 v[42:43], s[50:51], 0, v[2:3]
	v_lshl_add_u64 v[44:45], s[48:49], 0, v[2:3]
	v_lshl_or_b32 v46, v178, 9, v6
	s_lshl_b32 s42, s30, 12
	s_mov_b64 s[12:13], 0
	s_movk_i32 s43, 0x1200
	s_mov_b32 s48, 0x800000
	s_movk_i32 s49, 0xc00
	s_xor_b64 s[14:15], vcc, -1
	s_mov_b32 s50, 0x41a00000
	s_mov_b32 s51, 0x3fb8aa3b
	s_mov_b32 s52, 0xc2ce8ed0
	s_mov_b32 s53, 0x42b17218
	s_mov_b32 s54, 0x7f800000
	s_mov_b32 s55, 0x3f2aaaab
	v_mov_b32_e32 v35, 0x3ecc95a3
	s_mov_b32 s56, 0x3f317218
	s_mov_b32 s57, 0x33800000
	v_mov_b32_e32 v37, 0x3db504f3
	v_mov_b32_e32 v47, 0x7f800000
	v_mov_b32_e32 v48, 0x3f317218
	v_mov_b32_e32 v50, v178
	s_branch .LBB0_191
.LBB0_190:
	s_or_b64 exec, exec, s[8:9]
	v_add_u32_e32 v50, s35, v50
	s_movk_i32 s8, 0x2fff
	v_cmp_lt_i32_e32 vcc, s8, v50
	s_or_b64 s[12:13], vcc, s[12:13]
	v_add_u32_e32 v46, s42, v46
	s_andn2_b64 exec, exec, s[12:13]
	s_cbranch_execz .LBB0_240

.LBB0_203:
	s_or_b64 exec, exec, s[16:17]
	v_lshl_add_u64 v[64:65], v[64:65], 1, s[76:77]
	v_mul_f32_e32 v51, v122, v49
	v_cmp_eq_u32_e32 vcc, 0, v86
	v_mul_f32_e32 v53, v123, v49
	v_cvt_pk_bf16_f32 v122, v51, v53
	v_mul_f32_e32 v51, v126, v49
	v_mad_i64_i32 v[86:87], s[16:17], v70, s49, v[64:65]
	v_ashrrev_i32_e32 v71, 31, v70
	v_mul_f32_e32 v53, v127, v49
	v_cvt_pk_bf16_f32 v123, v51, v53
	v_mul_f32_e32 v51, v124, v49
	s_and_b64 s[16:17], vcc, s[14:15]
	v_mul_f32_e32 v53, v125, v49
	v_cvt_pk_bf16_f32 v124, v51, v53
	v_mul_f32_e32 v51, v120, v49
	v_mul_f32_e32 v49, v121, v49
	v_cvt_pk_bf16_f32 v125, v51, v49
	global_store_dwordx4 v[86:87], v[122:125], off
	s_and_saveexec_b64 s[18:19], s[16:17]
	s_branch .LBB0_211

.LBB0_213:
	s_or_b64 exec, exec, s[18:19]
	v_mul_f32_e32 v4, v4, v10
	v_mul_f32_e32 v5, v5, v10
	v_cvt_pk_bf16_f32 v4, v4, v5
	v_mul_f32_e32 v5, v8, v10
	v_mul_f32_e32 v6, v6, v10
	v_mul_f32_e32 v7, v7, v10
	v_mul_f32_e32 v2, v2, v10
	v_mul_f32_e32 v3, v3, v10
	v_mul_f32_e32 v8, v9, v10
	v_cvt_pk_bf16_f32 v5, v5, v8
	v_cvt_pk_bf16_f32 v6, v6, v7
	v_cvt_pk_bf16_f32 v7, v2, v3
	v_mad_i64_i32 v[2:3], s[18:19], v72, s49, v[64:65]
	global_store_dwordx4 v[2:3], v[4:7], off
	s_and_saveexec_b64 s[18:19], s[16:17]
	s_branch .LBB0_221

.LBB0_223:
	s_or_b64 exec, exec, s[18:19]
	v_mul_f32_e32 v2, v2, v10
	v_mul_f32_e32 v3, v3, v10
	v_cvt_pk_bf16_f32 v2, v2, v3
	v_mul_f32_e32 v3, v4, v10
	v_mul_f32_e32 v4, v5, v10
	v_cvt_pk_bf16_f32 v3, v3, v4
	v_mul_f32_e32 v4, v6, v10
	v_mul_f32_e32 v5, v7, v10
	v_cvt_pk_bf16_f32 v4, v4, v5
	v_mul_f32_e32 v5, v8, v10
	v_mul_f32_e32 v6, v9, v10
	v_cvt_pk_bf16_f32 v5, v5, v6
	v_mad_i64_i32 v[6:7], s[18:19], v60, s49, v[64:65]
	global_store_dwordx4 v[6:7], v[2:5], off
	s_and_saveexec_b64 s[18:19], s[16:17]
	s_branch .LBB0_231

.LBB0_233:
	s_or_b64 exec, exec, s[18:19]
	v_mul_f32_e32 v2, v2, v10
	v_mul_f32_e32 v3, v3, v10
	v_cvt_pk_bf16_f32 v2, v2, v3
	v_mul_f32_e32 v3, v4, v10
	v_mul_f32_e32 v4, v5, v10
	v_cvt_pk_bf16_f32 v3, v3, v4
	v_mul_f32_e32 v4, v6, v10
	v_mul_f32_e32 v5, v7, v10
	v_cvt_pk_bf16_f32 v4, v4, v5
	v_mul_f32_e32 v5, v8, v10
	v_mul_f32_e32 v6, v9, v10
	v_cvt_pk_bf16_f32 v5, v5, v6
	v_mad_i64_i32 v[6:7], s[8:9], v52, s49, v[64:65]
	global_store_dwordx4 v[6:7], v[2:5], off
	s_and_saveexec_b64 s[8:9], s[16:17]
	s_branch .LBB0_190
.LBB0_240:
	s_or_b64 exec, exec, s[10:11]
	v_readlane_b32 s20, v42, 1
	v_readlane_b32 s21, v43, 1
	v_readlane_b32 s22, v44, 1
	v_readlane_b32 s23, v45, 1
	v_lshl_add_u32 v2, s2, 9, v164
	v_and_b32_e32 v3, 3, v2
	v_bfe_u32 v34, v2, 2, 2
	v_lshrrev_b32_e32 v50, 4, v2
	v_lshl_add_u32 v36, v3, 2, v34
	v_cmp_ne_u32_e64 s[6:7], 0, v3
	v_cmp_gt_u32_e64 s[14:15], 3, v3
	v_add_u32_e32 v4, -4, v36
	v_mov_b32_e32 v5, 0
	v_lshlrev_b64 v[4:5], 2, v[4:5]
	v_lshl_add_u64 v[42:43], s[20:21], 0, v[4:5]
	v_lshl_add_u64 v[44:45], s[22:23], 0, v[4:5]
	v_lshlrev_b32_e32 v4, 4, v34
	v_lshl_add_u32 v4, v3, 2, v4
	v_mov_b32_e32 v5, 0
	s_add_u32 s18, s28, 0xfd00000
	s_addc_u32 s19, s29, 0
	v_lshl_add_u64 v[40:41], s[18:19], 0, v[4:5]
	v_mov_b32_e32 v53, 0
	v_mov_b32_e32 v71, 0
	v_mov_b32_e32 v38, 0
	s_mov_b32 s12, 0
	s_mov_b64 s[8:9], exec
	s_and_b64 exec, exec, s[14:15]
.Lgp_loop:
	v_mov_b32_e32 v52, v50
	v_mul_u32_u24_e32 v70, 0x1200, v50
	v_lshl_add_u64 v[2:3], s[0:1], 0, v[70:71]
	s_and_saveexec_b64 s[16:17], s[6:7]
	s_xor_b64 s[16:17], exec, s[16:17]
	s_cbranch_execz .Lgp_238
	v_lshlrev_b32_e32 v4, 1, v36
	v_mov_b32_e32 v5, v38
	v_lshl_add_u64 v[2:3], v[2:3], 0, v[4:5]
	global_load_ushort v2, v[2:3], off offset:4088
	s_nop 0
	global_load_dword v3, v[42:43], off
	s_waitcnt vmcnt(1)
	v_lshlrev_b32_e32 v2, 16, v2
	s_waitcnt vmcnt(0)
	v_add_f32_e32 v2, v3, v2
	v_cmp_nlt_f32_e32 vcc, s50, v2
	s_and_saveexec_b64 s[18:19], vcc
	s_cbranch_execz .Lgp_237
	v_mul_f32_e32 v3, 0x3fb8aa3b, v2
	v_rndne_f32_e32 v4, v3
	v_sub_f32_e32 v5, v3, v4
	v_fma_f32 v3, v2, s51, -v3
	v_fmac_f32_e32 v3, 0x32a5705f, v2
	v_add_f32_e32 v3, v5, v3
	v_cvt_i32_f32_e32 v4, v4
	v_exp_f32_e32 v3, v3
	v_cmp_ngt_f32_e32 vcc, s52, v2
	v_ldexp_f32 v3, v3, v4
	s_nop 0
	v_cndmask_b32_e32 v3, 0, v3, vcc
	v_cmp_nlt_f32_e32 vcc, s53, v2
	s_nop 1
	v_cndmask_b32_e32 v16, v47, v3, vcc
	v_add_f32_e32 v4, 1.0, v16
	v_add_f32_e32 v2, -1.0, v4
	v_sub_f32_e32 v3, v2, v4
	v_add_f32_e32 v3, 1.0, v3
	v_sub_f32_e32 v2, v16, v2
	v_add_f32_e32 v5, v2, v3
	v_frexp_mant_f32_e32 v6, v4
	v_cvt_f64_f32_e32 v[2:3], v4
	v_frexp_exp_i32_f64_e32 v2, v[2:3]
	v_cmp_gt_f32_e32 vcc, s55, v6
	s_nop 1
	v_subbrev_co_u32_e32 v10, vcc, 0, v2, vcc
	v_sub_u32_e32 v2, 0, v10
	v_ldexp_f32 v3, v4, v2
	v_add_f32_e32 v4, -1.0, v3
	v_add_f32_e32 v6, 1.0, v3
	v_ldexp_f32 v2, v5, v2
	v_add_f32_e32 v5, 1.0, v4
	v_add_f32_e32 v7, -1.0, v6
	v_sub_f32_e32 v5, v3, v5
	v_sub_f32_e32 v3, v3, v7
	v_add_f32_e32 v5, v2, v5
	v_add_f32_e32 v2, v2, v3
	v_add_f32_e32 v11, v6, v2
	v_rcp_f32_e32 v13, v11
	v_sub_f32_e32 v3, v6, v11
	v_add_f32_e32 v12, v2, v3
	v_add_f32_e32 v3, v4, v5
	v_mul_f32_e32 v15, v3, v13
	v_sub_f32_e32 v2, v4, v3
	v_mul_f32_e32 v4, v11, v15
	v_fma_f32 v6, v15, v11, -v4
	v_fmac_f32_e32 v6, v15, v12
	v_add_f32_e32 v14, v5, v2
	v_add_f32_e32 v2, v4, v6
	v_sub_f32_e32 v5, v3, v2
	v_pk_add_f32 v[8:9], v[2:3], v[4:5] neg_lo:[0,1] neg_hi:[0,1]
	v_mov_b32_e32 v7, v2
	v_pk_add_f32 v[2:3], v[8:9], v[6:7] neg_lo:[0,1] neg_hi:[0,1]
	v_cmp_neq_f32_e32 vcc, s54, v16
	v_add_f32_e32 v3, v14, v3
	v_add_f32_e32 v2, v2, v3
	v_add_f32_e32 v3, v5, v2
	v_mul_f32_e32 v14, v13, v3
	v_mul_f32_e32 v4, v11, v14
	v_fma_f32 v6, v14, v11, -v4
	v_fmac_f32_e32 v6, v14, v12
	v_sub_f32_e32 v5, v5, v3
	v_add_f32_e32 v11, v2, v5
	v_add_f32_e32 v2, v4, v6
	v_sub_f32_e32 v5, v3, v2
	v_pk_add_f32 v[8:9], v[2:3], v[4:5] neg_lo:[0,1] neg_hi:[0,1]
	v_mov_b32_e32 v7, v2
	v_pk_add_f32 v[2:3], v[8:9], v[6:7] neg_lo:[0,1] neg_hi:[0,1]
	s_nop 0
	v_add_f32_e32 v3, v11, v3
	v_add_f32_e32 v2, v2, v3
	v_add_f32_e32 v3, v15, v14
	v_add_f32_e32 v2, v5, v2
	v_sub_f32_e32 v4, v3, v15
	v_mul_f32_e32 v2, v13, v2
	v_sub_f32_e32 v4, v14, v4
	v_add_f32_e32 v4, v4, v2
	v_add_f32_e32 v6, v3, v4
	v_mul_f32_e32 v7, v6, v6
	v_fmamk_f32 v2, v7, 0x3e9b6dac, v35
	v_fmaak_f32 v49, v7, v2, 0x3f2aaada
	v_cvt_f32_i32_e32 v2, v10
	v_sub_f32_e32 v3, v6, v3
	v_sub_f32_e32 v3, v4, v3
	v_ldexp_f32 v8, v3, 1
	v_mul_f32_e32 v3, v6, v7
	v_ldexp_f32 v5, v6, 1
	v_pk_mul_f32 v[6:7], v[2:3], v[48:49]
	s_nop 0
	v_fma_f32 v4, v2, s56, -v6
	v_fmac_f32_e32 v4, 0xb102e308, v2
	v_pk_add_f32 v[2:3], v[6:7], v[4:5]
	s_nop 0
	v_sub_f32_e32 v5, v3, v5
	v_sub_f32_e32 v5, v7, v5
	v_add_f32_e32 v9, v8, v5
	v_mov_b32_e32 v8, v6
	v_pk_add_f32 v[6:7], v[2:3], v[6:7] neg_lo:[0,1] neg_hi:[0,1]
	v_pk_add_f32 v[10:11], v[2:3], v[8:9]
	v_mov_b32_e32 v5, v2
	v_mov_b32_e32 v7, v11
	v_pk_add_f32 v[12:13], v[4:5], v[6:7] neg_lo:[0,1] neg_hi:[0,1]
	v_pk_add_f32 v[4:5], v[4:5], v[6:7]
	v_mov_b32_e32 v8, v9
	v_pk_add_f32 v[6:7], v[4:5], v[2:3] op_sel:[1,0] op_sel_hi:[0,1] neg_lo:[0,1] neg_hi:[0,1]
	v_pk_add_f32 v[14:15], v[10:11], v[6:7] op_sel_hi:[1,0] neg_lo:[0,1] neg_hi:[0,1]
	v_mov_b32_e32 v10, v11
	v_mov_b32_e32 v11, v5
	v_pk_mov_b32 v[6:7], v[2:3], v[6:7] op_sel:[1,0]
	v_mov_b32_e32 v9, v2
	v_pk_add_f32 v[6:7], v[10:11], v[6:7] neg_lo:[0,1] neg_hi:[0,1]
	v_mov_b32_e32 v14, v12
	v_pk_add_f32 v[2:3], v[8:9], v[6:7] neg_lo:[0,1] neg_hi:[0,1]
	v_mov_b32_e32 v13, v5
	v_pk_add_f32 v[6:7], v[14:15], v[2:3]
	s_nop 0
	v_pk_add_f32 v[8:9], v[6:7], v[6:7] op_sel:[0,1] op_sel_hi:[1,0]
	s_nop 0
	v_pk_add_f32 v[4:5], v[4:5], v[8:9] op_sel:[1,0] op_sel_hi:[0,1]
	v_mov_b32_e32 v7, v4
	v_pk_add_f32 v[10:11], v[6:7], v[12:13] neg_lo:[0,1] neg_hi:[0,1]
	v_mov_b32_e32 v3, v8
	v_sub_f32_e32 v5, v6, v10
	v_pk_add_f32 v[2:3], v[2:3], v[10:11] neg_lo:[0,1] neg_hi:[0,1]
	v_sub_f32_e32 v5, v12, v5
	v_add_f32_e32 v2, v2, v5
	v_add_f32_e32 v2, v2, v3
	v_add_f32_e32 v2, v4, v2
	v_cndmask_b32_e32 v2, v47, v2, vcc
	v_cmp_lt_f32_e64 vcc, |v16|, s57
	s_nop 1
	v_cndmask_b32_e32 v2, v2, v16, vcc

.Lgp_189:
	s_or_b64 exec, exec, s[16:17]
	v_lshlrev_b64 v[2:3], 6, v[52:53]
	v_lshl_add_u64 v[2:3], v[40:41], 0, v[2:3]
	global_store_dword v[2:3], v4, off
	v_add_u32_e32 v50, 0x2000, v50
	s_add_i32 s12, s12, 1
	s_cmp_lt_u32 s12, 2
	s_cbranch_scc1 .Lgp_loop
	s_mov_b64 exec, s[8:9]
	s_waitcnt vmcnt(0)
	s_barrier
	s_mov_b64 s[0:1], exec
	v_readlane_b32 s6, v255, 11
	v_readlane_b32 s7, v255, 12
	s_and_b64 s[6:7], s[0:1], s[6:7]
	s_mov_b64 exec, s[6:7]
	s_cbranch_execz .LBB0_292
	s_add_i32 s6, 0, 0x20400
	v_mov_b32_e32 v2, s6
	s_waitcnt vmcnt(0) expcnt(0) lgkmcnt(0)
	ds_read_b32 v4, v2
	s_add_i32 s6, 0, 0x20404
	v_mov_b32_e32 v2, s6
	ds_read_b32 v2, v2
	s_waitcnt lgkmcnt(1)
	v_cmp_ne_u32_e32 vcc, 0, v4
	s_cbranch_vccnz .LBB0_256
	v_readlane_b32 s6, v255, 8
	s_mul_i32 s64, s31, s6
	s_add_u32 s6, s28, 0xff00200
	s_addc_u32 s7, s29, 0
	s_add_u32 s8, s28, 0xff00400
	s_addc_u32 s9, s29, 0
	s_add_u32 s10, s28, 0xff00500
	s_addc_u32 s11, s29, 0
	s_add_u32 s12, s28, 0xff00600
	s_addc_u32 s13, s29, 0
	s_add_u32 s14, s28, 0xff00700
	s_addc_u32 s15, s29, 0
	s_add_u32 s16, s28, 0xff00800
	s_addc_u32 s17, s29, 0
	s_add_u32 s18, s28, 0xff00900
	s_addc_u32 s19, s29, 0
	s_add_u32 s20, s28, 0xff00a00
	s_addc_u32 s21, s29, 0
	s_add_u32 s22, s28, 0xff00b00
	s_addc_u32 s23, s29, 0
	s_add_u32 s34, s28, 0xff00c00
	s_addc_u32 s35, s29, 0
	s_add_u32 s42, s28, 0xff00d00
	s_addc_u32 s43, s29, 0
	s_add_u32 s46, s28, 0xff00e00
	s_addc_u32 s47, s29, 0
	s_add_u32 s48, s28, 0xff00f00
	s_addc_u32 s49, s29, 0
	s_add_u32 s50, s28, 0xff01000
	s_addc_u32 s51, s29, 0
	s_add_u32 s52, s28, 0xff01100
	s_addc_u32 s53, s29, 0
	s_add_u32 s54, s28, 0xff01200
	s_addc_u32 s55, s29, 0
	s_add_u32 s56, s28, 0xff01300
	s_mul_i32 s64, s64, s30
	s_addc_u32 s57, s29, 0
	s_mov_b32 s65, 1
	v_mov_b32_e32 v18, 0
	s_branch .LBB0_244
